# attention: compact wait-count tree and block-selection table, scalar clamp, first-step fast path (no accumulator clearing / rescale, SrcC=0), finalize exchange via v_permlane32_swap
# speedup vs baseline: 1.0073x; 1.0032x over previous
; __device__ __forceinline__ void attn_chain(LAS unsigned char* lds, const bf16* Qb, const bf16* Kb, const bf16* Vb, bf16* Ob, float* lseb, int g0, int wave, int lane) {
;     ...
;     for (int d = 0; d < 4; ++d)
; #pragma unroll
;         for (int i = 0; i < 16; ++i) o[d][i] = 0.f;
;     ...
;             const bool valid = gk >= 0 && gk < 384 && (gk >> 7) == pq && (((gk & 127) >> shpq) == rq);
;             (void)dq; (void)lq;
;             if (valid) {
.Lattn_invalid:
	s_cmp_lg_u32 s15, 0
	s_cbranch_scc1 .LBB0_642
	v_mov_b64_e32 v[0:1], 0
	v_mov_b64_e32 v[2:3], 0
	v_mov_b64_e32 v[4:5], 0
	v_mov_b64_e32 v[6:7], 0
	v_mov_b64_e32 v[8:9], 0
	v_mov_b64_e32 v[10:11], 0
	v_mov_b64_e32 v[12:13], 0
	v_mov_b64_e32 v[14:15], 0
	v_mov_b64_e32 v[16:17], 0
	v_mov_b64_e32 v[18:19], 0
	v_mov_b64_e32 v[20:21], 0
	v_mov_b64_e32 v[22:23], 0
	v_mov_b64_e32 v[24:25], 0
	v_mov_b64_e32 v[26:27], 0
	v_mov_b64_e32 v[28:29], 0
	v_mov_b64_e32 v[30:31], 0
	v_mov_b64_e32 v[32:33], 0
	v_mov_b64_e32 v[34:35], 0
	v_mov_b64_e32 v[36:37], 0
	v_mov_b64_e32 v[38:39], 0
	v_mov_b64_e32 v[40:41], 0
	v_mov_b64_e32 v[42:43], 0
	v_mov_b64_e32 v[44:45], 0
	v_mov_b64_e32 v[46:47], 0
	v_mov_b64_e32 v[48:49], 0
	v_mov_b64_e32 v[50:51], 0
	v_mov_b64_e32 v[52:53], 0
	v_mov_b64_e32 v[54:55], 0
	v_mov_b64_e32 v[56:57], 0
	v_mov_b64_e32 v[58:59], 0
	v_mov_b64_e32 v[60:61], 0
	v_mov_b64_e32 v[62:63], 0
	s_branch .LBB0_642

; __device__ __forceinline__ void attn_chain(LAS unsigned char* lds, const bf16* Qb, const bf16* Kb, const bf16* Vb, bf16* Ob, float* lseb, int g0, int wave, int lane) {
;     ...
;                 float pmax = sa[0];
; #pragma unroll
;                 for (int i = 1; i < 16; ++i) pmax = fmaxf(pmax, sa[i]);
;                 pmax = fmaxf(pmax, shfl_xor_f(pmax, 32));
;                 const float mn = fmaxf(m_run, pmax), alpha = __builtin_amdgcn_exp2f(m_run - mn); m_run = mn;
;                 float ps = 0.f;
; #pragma unroll
;                 for (int i = 0; i < 16; ++i) { sa[i] = __builtin_amdgcn_exp2f(sa[i] - mn); ps += sa[i]; }
;                 l_run = l_run * alpha + ps;
; #pragma unroll
;                 for (int d = 0; d < 4; ++d)
; #pragma unroll
;                     for (int i = 0; i < 16; ++i) o[d][i] *= alpha;
;                 bf16x8 pa[2];
; #pragma unroll
;                 for (int s2 = 0; s2 < 2; ++s2) { v4u w; w.x = pk2(sa[8 * s2], sa[8 * s2 + 1]); w.y = pk2(sa[8 * s2 + 2], sa[8 * s2 + 3]); w.z = pk2(sa[8 * s2 + 4], sa[8 * s2 + 5]); w.w = pk2(sa[8 * s2 + 6], sa[8 * s2 + 7]);
;                     pa[s2] = __builtin_bit_cast(bf16x8, w); }
;                 const unsigned so_ = (unsigned)(uintptr_t)lds + (unsigned)(kk & 7) * 16384u + 8192u;
;                 s16x4 lo[2][4], hh[2][4];
; #pragma unroll
;                 for (int d = 0; d < 4; ++d) { const unsigned a0_ = trb[d][0] + so_, a1_ = trb[d][1] + so_;
;                     asm volatile("ds_read_b64_tr_b16 %0, %1" : "=&v"(lo[0][d]) : "v"(a0_) : "memory");
;                     asm volatile("ds_read_b64_tr_b16 %0, %1" : "=&v"(hh[0][d]) : "v"(a1_) : "memory");
;                     asm volatile("ds_read_b64_tr_b16 %0, %1 offset:4096" : "=&v"(lo[1][d]) : "v"(a0_) : "memory");
;                     asm volatile("ds_read_b64_tr_b16 %0, %1 offset:4096" : "=&v"(hh[1][d]) : "v"(a1_) : "memory"); }
;                 asm volatile("s_waitcnt lgkmcnt(0)" ::: "memory"); __builtin_amdgcn_sched_barrier(0);
; #pragma unroll
;                 for (int s2 = 0; s2 < 2; ++s2)
; #pragma unroll
;                     for (int d = 0; d < 4; ++d) { const bf16x8 vt = {lo[s2][d][0], lo[s2][d][1], lo[s2][d][2], lo[s2][d][3], hh[s2][d][0], hh[s2][d][1], hh[s2][d][2], hh[s2][d][3]};
;                         o[d] = __builtin_amdgcn_mfma_f32_32x32x16_bf16(vt, pa[s2], o[d], 0, 0, 0); }
.LBB0_641:
	s_add_i32 s2, s2, 0
	s_addk_i32 s2, 0x2000
	v_add_u32_e32 v214, s2, v159
	ds_read_b64_tr_b16 v[206:207], v214
	v_add_u32_e32 v215, s2, v160
	ds_read_b64_tr_b16 v[208:209], v215
	ds_read_b64_tr_b16 v[210:211], v214 offset:4096
	ds_read_b64_tr_b16 v[212:213], v215 offset:4096
	v_add_u32_e32 v214, s2, v161
	ds_read_b64_tr_b16 v[178:179], v214
	v_add_u32_e32 v215, s2, v162
	ds_read_b64_tr_b16 v[180:181], v215
	ds_read_b64_tr_b16 v[184:185], v214 offset:4096
	ds_read_b64_tr_b16 v[186:187], v215 offset:4096
	v_add_u32_e32 v214, s2, v163
	ds_read_b64_tr_b16 v[188:189], v214
	v_add_u32_e32 v215, s2, v164
	ds_read_b64_tr_b16 v[190:191], v215
	ds_read_b64_tr_b16 v[192:193], v214 offset:4096
	ds_read_b64_tr_b16 v[194:195], v215 offset:4096
	v_add_u32_e32 v214, s2, v165
	ds_read_b64_tr_b16 v[196:197], v214
	v_add_u32_e32 v215, s2, v166
	ds_read_b64_tr_b16 v[198:199], v215
	ds_read_b64_tr_b16 v[200:201], v214 offset:4096
	ds_read_b64_tr_b16 v[202:203], v215 offset:4096
	s_nop 5
	v_max_f32_e32 v170, v65, v65
	v_max_f32_e32 v171, v64, v64
	v_max_f32_e32 v170, v171, v170
	v_max3_f32 v170, v170, v66, v67
	v_max3_f32 v170, v170, v68, v69
	v_max3_f32 v170, v170, v70, v71
	v_max3_f32 v170, v170, v72, v73
	v_max3_f32 v170, v170, v74, v75
	v_max3_f32 v170, v170, v76, v77
	v_max3_f32 v170, v170, v78, v79
	v_mov_b32_e32 v171, v170
	s_nop 1
	v_permlane32_swap_b32_e32 v171, v170
	s_nop 1
	v_max3_f32 v183, v149, v170, v171
	v_sub_f32_e32 v64, v64, v183
	v_exp_f32_e32 v170, v64
	v_sub_f32_e32 v64, v65, v183
	v_exp_f32_e32 v65, v64
	v_sub_f32_e32 v64, v66, v183
	v_exp_f32_e32 v171, v64
	v_sub_f32_e32 v64, v67, v183
	v_sub_f32_e32 v66, v78, v183
	v_exp_f32_e32 v67, v64
	v_sub_f32_e32 v64, v68, v183
	v_exp_f32_e32 v78, v66
	v_sub_f32_e32 v66, v79, v183
	v_exp_f32_e32 v68, v64
	v_sub_f32_e32 v64, v69, v183
	v_exp_f32_e32 v79, v66
	v_add_f32_e32 v66, 0, v170
	v_exp_f32_e32 v69, v64
	v_sub_f32_e32 v64, v70, v183
	v_add_f32_e32 v66, v65, v66
	v_exp_f32_e32 v70, v64
	v_sub_f32_e32 v64, v71, v183
	v_add_f32_e32 v66, v171, v66
	v_exp_f32_e32 v71, v64
	v_sub_f32_e32 v64, v72, v183
	v_add_f32_e32 v66, v67, v66
	v_exp_f32_e32 v72, v64
	v_sub_f32_e32 v64, v73, v183
	v_add_f32_e32 v66, v68, v66
	v_exp_f32_e32 v73, v64
	v_sub_f32_e32 v64, v74, v183
	v_add_f32_e32 v66, v69, v66
	v_exp_f32_e32 v74, v64
	v_sub_f32_e32 v64, v75, v183
	v_add_f32_e32 v66, v70, v66
	v_exp_f32_e32 v75, v64
	v_sub_f32_e32 v64, v76, v183
	v_add_f32_e32 v66, v71, v66
	v_exp_f32_e32 v76, v64
	v_sub_f32_e32 v64, v77, v183
	v_add_f32_e32 v66, v72, v66
	v_exp_f32_e32 v77, v64
	v_add_f32_e32 v66, v73, v66
	v_sub_f32_e32 v149, v149, v183
	v_add_f32_e32 v66, v74, v66
	v_exp_f32_e32 v64, v149
	v_add_f32_e32 v66, v75, v66
	v_add_f32_e32 v66, v76, v66
	v_add_f32_e32 v66, v77, v66
	v_add_f32_e32 v66, v78, v66
	s_cmp_eq_u32 s15, 0
	s_cbranch_scc1 .Lattn_noscale
	v_pk_mul_f32 v[62:63], v[62:63], v[64:65] op_sel_hi:[1,0]
	v_pk_mul_f32 v[60:61], v[60:61], v[64:65] op_sel_hi:[1,0]
	v_pk_mul_f32 v[58:59], v[58:59], v[64:65] op_sel_hi:[1,0]
	v_pk_mul_f32 v[56:57], v[56:57], v[64:65] op_sel_hi:[1,0]
	v_pk_mul_f32 v[54:55], v[54:55], v[64:65] op_sel_hi:[1,0]
	v_pk_mul_f32 v[52:53], v[52:53], v[64:65] op_sel_hi:[1,0]
	v_pk_mul_f32 v[50:51], v[50:51], v[64:65] op_sel_hi:[1,0]
	v_pk_mul_f32 v[48:49], v[48:49], v[64:65] op_sel_hi:[1,0]
	v_pk_mul_f32 v[46:47], v[46:47], v[64:65] op_sel_hi:[1,0]
	v_pk_mul_f32 v[44:45], v[44:45], v[64:65] op_sel_hi:[1,0]
	v_pk_mul_f32 v[42:43], v[42:43], v[64:65] op_sel_hi:[1,0]
	v_pk_mul_f32 v[40:41], v[40:41], v[64:65] op_sel_hi:[1,0]
	v_pk_mul_f32 v[38:39], v[38:39], v[64:65] op_sel_hi:[1,0]
	v_pk_mul_f32 v[36:37], v[36:37], v[64:65] op_sel_hi:[1,0]
	v_pk_mul_f32 v[34:35], v[34:35], v[64:65] op_sel_hi:[1,0]
	v_pk_mul_f32 v[32:33], v[32:33], v[64:65] op_sel_hi:[1,0]
	v_pk_mul_f32 v[30:31], v[30:31], v[64:65] op_sel_hi:[1,0]
	v_pk_mul_f32 v[28:29], v[28:29], v[64:65] op_sel_hi:[1,0]
	v_pk_mul_f32 v[26:27], v[26:27], v[64:65] op_sel_hi:[1,0]
	v_pk_mul_f32 v[24:25], v[24:25], v[64:65] op_sel_hi:[1,0]
	v_pk_mul_f32 v[22:23], v[22:23], v[64:65] op_sel_hi:[1,0]
	v_pk_mul_f32 v[20:21], v[20:21], v[64:65] op_sel_hi:[1,0]
	v_pk_mul_f32 v[18:19], v[18:19], v[64:65] op_sel_hi:[1,0]
	v_pk_mul_f32 v[16:17], v[16:17], v[64:65] op_sel_hi:[1,0]
	v_pk_mul_f32 v[14:15], v[14:15], v[64:65] op_sel_hi:[1,0]
	v_pk_mul_f32 v[12:13], v[12:13], v[64:65] op_sel_hi:[1,0]
	v_pk_mul_f32 v[10:11], v[10:11], v[64:65] op_sel_hi:[1,0]
	v_pk_mul_f32 v[8:9], v[8:9], v[64:65] op_sel_hi:[1,0]
	v_pk_mul_f32 v[6:7], v[6:7], v[64:65] op_sel_hi:[1,0]
	v_pk_mul_f32 v[4:5], v[4:5], v[64:65] op_sel_hi:[1,0]
	v_pk_mul_f32 v[2:3], v[2:3], v[64:65] op_sel_hi:[1,0]
	v_pk_mul_f32 v[0:1], v[0:1], v[64:65] op_sel_hi:[1,0]
.Lattn_noscale:
	v_add_f32_e32 v204, v79, v66
	v_cvt_pk_bf16_f32 v66, v170, v65
	v_cvt_pk_bf16_f32 v68, v68, v69
	v_cvt_pk_bf16_f32 v69, v70, v71
	v_cvt_pk_bf16_f32 v71, v74, v75
	v_cvt_pk_bf16_f32 v70, v72, v73
	v_cvt_pk_bf16_f32 v72, v76, v77
	v_cvt_pk_bf16_f32 v73, v78, v79
	v_cvt_pk_bf16_f32 v67, v171, v67
	s_nop 1
	s_waitcnt lgkmcnt(0)
	s_cmp_eq_u32 s15, 0
	s_cbranch_scc1 .Lattn_pv_first
	v_mfma_f32_32x32x16_bf16 v[48:63], v[206:209], v[66:69], v[48:63]
	v_fmac_f32_e32 v204, v182, v64
	v_mov_b32_e32 v149, v183
	v_mov_b32_e32 v182, v204
	v_mfma_f32_32x32x16_bf16 v[32:47], v[178:181], v[66:69], v[32:47]
	v_mfma_f32_32x32x16_bf16 v[16:31], v[188:191], v[66:69], v[16:31]
	v_mfma_f32_32x32x16_bf16 v[0:15], v[196:199], v[66:69], v[0:15]
	s_branch .Lattn_pv_rest
.Lattn_pv_first:
	v_mfma_f32_32x32x16_bf16 v[48:63], v[206:209], v[66:69], 0
	v_fmac_f32_e32 v204, v182, v64
	v_mov_b32_e32 v149, v183
	v_mov_b32_e32 v182, v204
	v_mfma_f32_32x32x16_bf16 v[32:47], v[178:181], v[66:69], 0
	v_mfma_f32_32x32x16_bf16 v[16:31], v[188:191], v[66:69], 0
	v_mfma_f32_32x32x16_bf16 v[0:15], v[196:199], v[66:69], 0
.Lattn_pv_rest:
	v_mfma_f32_32x32x16_bf16 v[48:63], v[210:213], v[70:73], v[48:63]
	v_mfma_f32_32x32x16_bf16 v[32:47], v[184:187], v[70:73], v[32:47]
	v_mfma_f32_32x32x16_bf16 v[16:31], v[192:195], v[70:73], v[16:31]
	v_mfma_f32_32x32x16_bf16 v[0:15], v[200:203], v[70:73], v[0:15]

; __device__ __forceinline__ void attn_chain(LAS unsigned char* lds, const bf16* Qb, const bf16* Kb, const bf16* Vb, bf16* Ob, float* lseb, int g0, int wave, int lane) {
;     ...
;         const int rel = s - cw; const bool act = rel >= 0 && rel < 5 * NJOB;
;         const int n = act ? rel / 5 : 0, t = act ? rel - 5 * n : 3;
;         { const int y = p1 + ((act && n > 0 && (t == 1 || t == 2)) ? 9 : (act && t == 4 && n + 1 < NJOB) ? 8 : 0);
;           if (y == 2) asm volatile("s_waitcnt vmcnt(2) lgkmcnt(0)" ::: "memory");
;           else if (y == 4) asm volatile("s_waitcnt vmcnt(4) lgkmcnt(0)" ::: "memory");
;           else if (y == 8) asm volatile("s_waitcnt vmcnt(8) lgkmcnt(0)" ::: "memory");
;           else if (y == 10) asm volatile("s_waitcnt vmcnt(10) lgkmcnt(0)" ::: "memory");
;           else if (y == 12) asm volatile("s_waitcnt vmcnt(12) lgkmcnt(0)" ::: "memory");
;           else if (y == 9) asm volatile("s_waitcnt vmcnt(9) lgkmcnt(0)" ::: "memory");
;           else if (y == 11) asm volatile("s_waitcnt vmcnt(11) lgkmcnt(0)" ::: "memory");
;           else if (y == 13) asm volatile("s_waitcnt vmcnt(13) lgkmcnt(0)" ::: "memory");
;           else asm volatile("s_waitcnt vmcnt(0) lgkmcnt(0)" ::: "memory"); }
;         if (act && t == 0) {
;             asm volatile("" : "+v"(qn[0]), "+v"(qn[1]), "+v"(qn[2]), "+v"(qn[3]), "+v"(qn[4]), "+v"(qn[5]), "+v"(qn[6]), "+v"(qn[7]));
; #pragma unroll
;             for (int s2 = 0; s2 < 8; ++s2) qf[s2] = qn[s2];
;         }
;         __builtin_amdgcn_s_barrier();
;         asm volatile("" ::: "memory");
;         { int k0, k1 = -1;
;           if (ph == 0) k0 = 8 * mm + 4; else if (ph == 1) { k0 = 8 * mm + 5; k1 = k0 + 1; } else if (ph == 2) k0 = 8 * mm + 7; else if (ph == 3) { k0 = 8 * mm + 8; k1 = k0 + 1; } else { k0 = 8 * mm + 10; k1 = k0 + 1; }
;           p1 = 0;
;           if (k0 < NKB) { AC_ISSUE(k0); p1 = 2; }
;           if (k1 >= 0 && k1 < NKB) { AC_ISSUE(k1); p1 += 2; } }
.LBB0_643:
	s_and_b32 s2, s84, 0xff
	s_mulk_i32 s2, 0xcd
	s_lshr_b32 s2, s2, 10
	s_cmp_lt_u32 s84, 30
	s_cselect_b64 s[6:7], -1, 0
	s_and_b64 s[6:7], s[6:7], exec
	s_cselect_b32 s14, s2, 0
	s_mul_i32 s30, s14, -5
	s_add_i32 s15, s84, s30
	s_cmp_lt_u32 s84, 30
	s_cselect_b64 s[6:7], -1, 0
	s_and_b64 s[12:13], s[6:7], exec
	s_cselect_b32 s3, s15, 3
	s_cmp_lg_u32 s14, 0
	s_cselect_b64 s[70:71], -1, 0
	s_add_i32 s12, s3, -1
	s_cmp_lt_u32 s12, 2
	s_cselect_b64 s[12:13], -1, 0
	s_and_b64 s[12:13], s[6:7], s[12:13]
	s_and_b64 s[12:13], s[12:13], s[70:71]
	s_cmp_eq_u32 s3, 4
	s_cselect_b64 s[42:43], -1, 0
	s_and_b64 s[42:43], s[6:7], s[42:43]
	s_cmp_eq_u32 s14, 5
	s_cselect_b32 s31, 0, 8
	s_and_b64 s[42:43], s[42:43], exec
	s_cselect_b32 s31, s31, 0
	s_and_b64 s[12:13], s[12:13], exec
	s_cselect_b32 s33, 9, s31
	s_add_i32 s33, s33, s74
	s_cmp_lt_i32 s33, 9
	s_cbranch_scc1 .Lattn_wlo
	s_cmp_lt_i32 s33, 11
	s_cbranch_scc1 .Lattn_w9_10
	s_cmp_lt_i32 s33, 13
	s_cbranch_scc1 .Lattn_w11_12
	s_cmp_eq_u32 s33, 13
	s_cbranch_scc0 .Lattn_w0
	s_waitcnt vmcnt(13) lgkmcnt(0)
	s_branch .LBB0_669
.Lattn_w11_12:
	s_cmp_eq_u32 s33, 11
	s_cbranch_scc1 .Lattn_w11
	s_waitcnt vmcnt(12) lgkmcnt(0)
	s_branch .LBB0_669
.Lattn_w11:
	s_waitcnt vmcnt(11) lgkmcnt(0)
	s_branch .LBB0_669
.Lattn_w9_10:
	s_cmp_eq_u32 s33, 9
	s_cbranch_scc1 .Lattn_w9
	s_waitcnt vmcnt(10) lgkmcnt(0)
	s_branch .LBB0_669
.Lattn_w9:
	s_waitcnt vmcnt(9) lgkmcnt(0)
	s_branch .LBB0_669
.Lattn_wlo:
	s_cmp_eq_u32 s33, 4
	s_cbranch_scc1 .Lattn_w4
	s_cmp_eq_u32 s33, 2
	s_cbranch_scc1 .Lattn_w2
	s_cmp_eq_u32 s33, 8
	s_cbranch_scc0 .Lattn_w0
	s_waitcnt vmcnt(8) lgkmcnt(0)
	s_branch .LBB0_669
.Lattn_w4:
	s_waitcnt vmcnt(4) lgkmcnt(0)
	s_branch .LBB0_669
.Lattn_w2:
	s_waitcnt vmcnt(2) lgkmcnt(0)
	s_branch .LBB0_669
.Lattn_w0:
	s_waitcnt vmcnt(0) lgkmcnt(0)
.LBB0_669:
	s_cmp_eq_u32 s3, 0
	s_cselect_b64 s[72:73], -1, 0
	s_and_b64 s[12:13], s[6:7], s[72:73]
	s_andn2_b64 vcc, exec, s[12:13]
	s_cbranch_vccnz .LBB0_671
	s_nop 0
	v_mov_b64_e32 v[114:115], v[82:83]
	v_mov_b64_e32 v[118:119], v[86:87]
	v_mov_b64_e32 v[122:123], v[90:91]
	v_mov_b64_e32 v[126:127], v[94:95]
	v_mov_b64_e32 v[130:131], v[98:99]
	v_mov_b64_e32 v[134:135], v[102:103]
	v_mov_b64_e32 v[138:139], v[106:107]
	v_mov_b64_e32 v[142:143], v[110:111]
	v_mov_b64_e32 v[112:113], v[80:81]
	v_mov_b64_e32 v[116:117], v[84:85]
	v_mov_b64_e32 v[120:121], v[88:89]
	v_mov_b64_e32 v[124:125], v[92:93]
	v_mov_b64_e32 v[128:129], v[96:97]
	v_mov_b64_e32 v[132:133], v[100:101]
	v_mov_b64_e32 v[136:137], v[104:105]
	v_mov_b64_e32 v[140:141], v[108:109]
.LBB0_671:
	s_barrier
	s_mul_i32 s100, s14, 0xfffec000
	s_add_i32 s100, s82, s100
	s_and_b32 s100, s100, 0x1c000
	v_add_u32_e32 v216, s100, v158
	v_xad_u32 v217, v216, 16, 0
	ds_read_b128 v[220:223], v216
	ds_read_b128 v[170:173], v217
	v_xad_u32 v217, v216, 32, 0
	v_xad_u32 v218, v216, 48, 0
	ds_read_b128 v[178:181], v217
	ds_read_b128 v[184:187], v218
	v_xad_u32 v217, v216, 64, 0
	v_xor_b32_e32 v218, 0x50, v216
	ds_read_b128 v[188:191], v217
	ds_read_b128 v[192:195], v218
	v_xor_b32_e32 v217, 0x60, v216
	v_xor_b32_e32 v218, 0x70, v216
	ds_read_b128 v[196:199], v217
	ds_read_b128 v[200:203], v218
	s_lshl_b32 s42, s85, 3
	s_lshl_b32 s12, s86, 2
	s_lshr_b32 s40, 0xa8754, s12
	s_and_b32 s40, s40, 15
	s_add_i32 s40, s40, s42
	s_lshr_b32 s12, 26, s86
	s_and_b32 s12, s12, 1
	s_add_i32 s33, s40, 1
	s_cmp_eq_u32 s12, 0
	s_cselect_b32 s33, -1, s33

.LBB0_688:
	s_add_i32 s12, s33, s10
	s_max_i32 s12, s12, 2
	s_add_i32 s74, s74, 2
	s_min_i32 s12, s12, 0x181
	s_add_i32 s12, s12, -2
	s_lshr_b32 s13, s12, 6
	s_and_b32 s13, s13, 0x3fffffe
	s_sub_i32 s31, 7, s13
	s_and_b32 s40, s12, 0x7f
	s_lshr_b32 s40, s40, s31
	s_lshl_b32 s31, -1, s31
	s_andn2_b32 s12, s12, s31
	v_lshl_add_u32 v64, s12, 5, v156
	v_lshlrev_b32_e32 v64, s13, v64
	v_add_u32_e32 v64, s40, v64
	s_lshl_b32 s12, s33, 14
	v_ashrrev_i32_e32 v65, 31, v64
	s_and_b32 s12, s12, 0x1c000
	s_add_i32 s12, s94, s12
	v_lshlrev_b64 v[64:65], 11, v[64:65]
	v_lshl_add_u64 v[66:67], v[150:151], 0, v[64:65]
	s_mov_b32 m0, s12
	v_lshl_add_u64 v[64:65], v[152:153], 0, v[64:65]
	global_load_lds_dwordx4 v[66:67], off
	s_add_i32 m0, s12, 0x2000
	s_nop 0
	global_load_lds_dwordx4 v[64:65], off

.LBB0_691:
	s_andn2_b64 vcc, exec, s[6:7]
	s_cbranch_vccnz .LBB0_642
	s_and_b64 s[6:7], s[70:71], s[72:73]
	s_andn2_b64 vcc, exec, s[6:7]
	s_lshl_b32 s2, s2, 3
	s_cbranch_vccnz .LBB0_696
	s_add_i32 s3, s80, s2
	v_mov_b32_e32 v64, v182
	s_nop 1
	v_permlane32_swap_b32_e32 v64, v182
	s_nop 1
	s_ashr_i32 s6, s3, 7
	s_lshl_b32 s7, s6, 1
	s_sub_i32 s12, 7, s7
	s_and_b32 s13, s3, 0x7f
	s_lshr_b32 s31, s13, s12
	s_lshl_b32 s12, -1, s12
	s_waitcnt lgkmcnt(0)
	v_add_f32_e32 v66, v182, v64
	s_andn2_b32 s3, s3, s12
	v_div_scale_f32 v65, s[12:13], v66, v66, 1.0
	v_rcp_f32_e32 v67, v65
	v_lshl_or_b32 v64, s3, 5, v157
	v_lshlrev_b32_e32 v64, s7, v64
	s_ashr_i32 s7, s6, 31
	v_fma_f32 v68, -v65, v67, 1.0
	v_fmac_f32_e32 v67, v68, v67
	v_div_scale_f32 v68, vcc, 1.0, v66, 1.0
	v_mul_f32_e32 v69, v68, v67
	v_fma_f32 v70, -v65, v69, v68
	v_fmac_f32_e32 v69, v70, v67
	v_fma_f32 v65, -v65, v69, v68
	v_div_fmas_f32 v65, v65, v67, v69
	v_add_u32_e32 v64, s31, v64
	v_div_fixup_f32 v68, v65, v66, 1.0
	s_lshl_b64 s[12:13], s[6:7], 25
	s_add_u32 s12, s28, s12
	v_ashrrev_i32_e32 v65, 31, v64
	v_pk_mul_f32 v[48:49], v[48:49], v[68:69] op_sel_hi:[1,0]
	v_pk_mul_f32 v[50:51], v[50:51], v[68:69] op_sel_hi:[1,0]
	v_pk_mul_f32 v[32:33], v[32:33], v[68:69] op_sel_hi:[1,0]
	v_pk_mul_f32 v[34:35], v[34:35], v[68:69] op_sel_hi:[1,0]
	v_pk_mul_f32 v[16:17], v[16:17], v[68:69] op_sel_hi:[1,0]
	v_pk_mul_f32 v[18:19], v[18:19], v[68:69] op_sel_hi:[1,0]
	v_pk_mul_f32 v[0:1], v[0:1], v[68:69] op_sel_hi:[1,0]
	v_pk_mul_f32 v[2:3], v[2:3], v[68:69] op_sel_hi:[1,0]
	s_addc_u32 s13, s57, s13
	v_lshlrev_b64 v[70:71], 11, v[64:65]
	v_cvt_pk_bf16_f32 v48, v48, v49
	v_cvt_pk_bf16_f32 v49, v50, v51
	v_pk_mul_f32 v[50:51], v[52:53], v[68:69] op_sel_hi:[1,0]
	v_pk_mul_f32 v[52:53], v[54:55], v[68:69] op_sel_hi:[1,0]
	v_cvt_pk_bf16_f32 v32, v32, v33
	v_cvt_pk_bf16_f32 v33, v34, v35
	v_pk_mul_f32 v[34:35], v[36:37], v[68:69] op_sel_hi:[1,0]
	v_pk_mul_f32 v[36:37], v[38:39], v[68:69] op_sel_hi:[1,0]
	v_cvt_pk_bf16_f32 v16, v16, v17
	v_cvt_pk_bf16_f32 v17, v18, v19
	v_pk_mul_f32 v[18:19], v[20:21], v[68:69] op_sel_hi:[1,0]
	v_pk_mul_f32 v[20:21], v[22:23], v[68:69] op_sel_hi:[1,0]
	v_cvt_pk_bf16_f32 v0, v0, v1
	v_cvt_pk_bf16_f32 v1, v2, v3
	v_pk_mul_f32 v[2:3], v[4:5], v[68:69] op_sel_hi:[1,0]
	v_pk_mul_f32 v[4:5], v[6:7], v[68:69] op_sel_hi:[1,0]
	v_lshl_add_u64 v[70:71], s[12:13], 0, v[70:71]
	v_cvt_pk_bf16_f32 v50, v50, v51
	v_cvt_pk_bf16_f32 v51, v52, v53
	v_cvt_pk_bf16_f32 v34, v34, v35
	v_cvt_pk_bf16_f32 v35, v36, v37
	v_cvt_pk_bf16_f32 v18, v18, v19
	v_cvt_pk_bf16_f32 v19, v20, v21
	v_cvt_pk_bf16_f32 v2, v2, v3
	v_cvt_pk_bf16_f32 v3, v4, v5
	v_lshl_add_u64 v[70:71], v[144:145], 1, v[70:71]
	v_permlane32_swap_b32_e32 v48, v50
	v_permlane32_swap_b32_e32 v49, v51
	v_permlane32_swap_b32_e32 v32, v34
	v_permlane32_swap_b32_e32 v33, v35
	v_permlane32_swap_b32_e32 v16, v18
	v_permlane32_swap_b32_e32 v17, v19
	v_permlane32_swap_b32_e32 v0, v2
	v_permlane32_swap_b32_e32 v1, v3
	global_store_dwordx4 v[70:71], v[48:51], off
	global_store_dwordx4 v[70:71], v[32:35], off offset:64
	global_store_dwordx4 v[70:71], v[16:19], off offset:128
	v_pk_mul_f32 v[48:49], v[56:57], v[68:69] op_sel_hi:[1,0]
	v_pk_mul_f32 v[50:51], v[58:59], v[68:69] op_sel_hi:[1,0]
	v_pk_mul_f32 v[32:33], v[40:41], v[68:69] op_sel_hi:[1,0]
	v_pk_mul_f32 v[34:35], v[42:43], v[68:69] op_sel_hi:[1,0]
	v_pk_mul_f32 v[16:17], v[24:25], v[68:69] op_sel_hi:[1,0]
	v_pk_mul_f32 v[18:19], v[26:27], v[68:69] op_sel_hi:[1,0]
	global_store_dwordx4 v[70:71], v[0:3], off offset:192
	v_cvt_pk_bf16_f32 v48, v48, v49
	v_cvt_pk_bf16_f32 v49, v50, v51
	v_pk_mul_f32 v[0:1], v[8:9], v[68:69] op_sel_hi:[1,0]
	v_pk_mul_f32 v[2:3], v[10:11], v[68:69] op_sel_hi:[1,0]
	v_pk_mul_f32 v[50:51], v[60:61], v[68:69] op_sel_hi:[1,0]
	v_pk_mul_f32 v[52:53], v[62:63], v[68:69] op_sel_hi:[1,0]
	v_cvt_pk_bf16_f32 v32, v32, v33
	v_cvt_pk_bf16_f32 v33, v34, v35
	v_pk_mul_f32 v[34:35], v[44:45], v[68:69] op_sel_hi:[1,0]
	v_pk_mul_f32 v[36:37], v[46:47], v[68:69] op_sel_hi:[1,0]
	v_cvt_pk_bf16_f32 v16, v16, v17
	v_cvt_pk_bf16_f32 v17, v18, v19
	v_pk_mul_f32 v[18:19], v[28:29], v[68:69] op_sel_hi:[1,0]
	v_pk_mul_f32 v[20:21], v[30:31], v[68:69] op_sel_hi:[1,0]
	v_cvt_pk_bf16_f32 v0, v0, v1
	v_cvt_pk_bf16_f32 v1, v2, v3
	v_pk_mul_f32 v[2:3], v[12:13], v[68:69] op_sel_hi:[1,0]
	v_pk_mul_f32 v[4:5], v[14:15], v[68:69] op_sel_hi:[1,0]
	v_cvt_pk_bf16_f32 v50, v50, v51
	v_cvt_pk_bf16_f32 v51, v52, v53
	v_cvt_pk_bf16_f32 v34, v34, v35
	v_cvt_pk_bf16_f32 v35, v36, v37
	v_cvt_pk_bf16_f32 v18, v18, v19
	v_cvt_pk_bf16_f32 v19, v20, v21
	v_cvt_pk_bf16_f32 v2, v2, v3
	v_cvt_pk_bf16_f32 v3, v4, v5
	v_permlane32_swap_b32_e32 v48, v50
	v_permlane32_swap_b32_e32 v49, v51
	v_permlane32_swap_b32_e32 v32, v34
	v_permlane32_swap_b32_e32 v33, v35
	v_permlane32_swap_b32_e32 v16, v18
	v_permlane32_swap_b32_e32 v17, v19
	v_permlane32_swap_b32_e32 v0, v2
	v_permlane32_swap_b32_e32 v1, v3
	global_store_dwordx4 v[70:71], v[48:51], off offset:32
	global_store_dwordx4 v[70:71], v[32:35], off offset:96
	global_store_dwordx4 v[70:71], v[16:19], off offset:160
	global_store_dwordx4 v[70:71], v[0:3], off offset:224
	s_and_saveexec_b64 s[70:71], s[4:5]
	s_cbranch_execz .LBB0_695
	v_cmp_gt_f32_e32 vcc, s93, v66
	s_lshl_b64 s[6:7], s[6:7], 19
	s_add_u32 s6, s22, s6
	v_cndmask_b32_e64 v0, 0, 32, vcc
	v_ldexp_f32 v0, v66, v0
	v_log_f32_e32 v2, v0
	v_cndmask_b32_e32 v3, 0, v236, vcc
	s_addc_u32 s7, s23, s7
	v_lshlrev_b64 v[0:1], 5, v[64:65]
	v_sub_f32_e32 v2, v2, v3
	v_lshl_add_u64 v[0:1], s[6:7], 0, v[0:1]
	v_add_f32_e32 v2, v149, v2
	global_store_dword v[0:1], v2, off
; #define LAS __attribute__((address_space(3)))
; __device__ __forceinline__ void attn_chain(LAS unsigned char* lds, const bf16* Qb, const bf16* Kb, const bf16* Vb, bf16* Ob, float* lseb, int g0, int wave, int lane) {
;     ...
;             const int L = wave + 8 * n, kk = L + t, gq = g0 + L, gk = gq - 2 + t;
;             AC_MAP(gq, pq, dq, rq, lq);
;             const bool valid = gk >= 0 && gk < 384 && (gk >> 7) == pq && (((gk & 127) >> shpq) == rq);
;             (void)dq; (void)lq;
;             if (valid) {
;                 const unsigned kb_ = kbl + (unsigned)(kk & 7) * 16384u;
;                 bf16x8 kf[8];
; #pragma unroll
;                 for (int s2 = 0; s2 < 8; ++s2) kf[s2] = *(const LAS bf16x8*)(lds + (kb_ ^ ((unsigned)s2 << 4)));
;                 f32x16 sa;
; #pragma unroll
;                 for (int i = 0; i < 16; ++i) sa[i] = 0.f;
;                 __builtin_amdgcn_sched_barrier(0); asm volatile("s_waitcnt lgkmcnt(0)" ::: "memory"); __builtin_amdgcn_sched_barrier(0);
; #pragma unroll
;                 for (int s2 = 0; s2 < 8; ++s2) sa = __builtin_amdgcn_mfma_f32_32x32x16_bf16(kf[s2], qf[s2], sa, 0, 0, 0);
.LBB0_695:
	s_or_b64 exec, exec, s[70:71]
	v_mov_b32_e32 v182, 0
	v_mov_b32_e32 v149, 0xf149f2ca
.LBB0_696:
	s_and_b32 s3, s83, 0xff
	s_mul_hi_u32 s3, s3, 0x33333334
	s_lshl_b32 s3, s3, 3
	s_add_i32 s3, s59, s3
	s_add_i32 s2, s2, s66
	s_add_i32 s30, s30, s3
	s_lshr_b32 s3, s2, 7
	s_cmpk_gt_u32 s30, 0x17f
	s_cselect_b64 s[6:7], -1, 0
	s_lshr_b32 s12, s30, 7
	s_cmp_lg_u32 s12, s3
	s_cselect_b64 s[12:13], -1, 0
	s_or_b64 s[6:7], s[6:7], s[12:13]
	s_and_b64 vcc, exec, s[6:7]
	s_cbranch_vccnz .Lattn_invalid
	s_lshl_b32 s3, s3, 1
	s_and_b32 s2, s2, 0x7f
	s_sub_i32 s3, 7, s3
	s_and_b32 s6, s30, 0x7f
	s_lshr_b32 s2, s2, s3
	s_lshr_b32 s3, s6, s3
	s_cmp_lg_u32 s3, s2
	s_cbranch_scc1 .Lattn_invalid
	s_mul_i32 s2, s14, 0xfffec000
	s_add_i32 s2, s82, s2
	s_and_b32 s2, s2, 0x1c000
	s_waitcnt lgkmcnt(0)
	s_waitcnt lgkmcnt(0)
	v_mfma_f32_32x32x16_bf16 v[64:79], v[220:223], v[112:115], 0
	s_cmp_lt_i32 s15, 4
	v_mfma_f32_32x32x16_bf16 v[64:79], v[170:173], v[116:119], v[64:79]
	v_mfma_f32_32x32x16_bf16 v[64:79], v[178:181], v[120:123], v[64:79]
	v_mfma_f32_32x32x16_bf16 v[64:79], v[184:187], v[124:127], v[64:79]
	v_mfma_f32_32x32x16_bf16 v[64:79], v[188:191], v[128:131], v[64:79]
	v_mfma_f32_32x32x16_bf16 v[64:79], v[192:195], v[132:135], v[64:79]
	v_mfma_f32_32x32x16_bf16 v[64:79], v[196:199], v[136:139], v[64:79]
	v_mfma_f32_32x32x16_bf16 v[64:79], v[200:203], v[140:143], v[64:79]
	s_cbranch_scc1 .LBB0_708
	s_cmp_eq_u32 s15, 4
	s_cselect_b64 s[6:7], -1, 0
	s_cbranch_execz .LBB0_709
	s_branch .LBB0_710
.LBB0_702:
	s_add_i32 s12, s40, s10
	s_max_i32 s12, s12, 2
	s_mov_b32 s74, 2
	s_min_i32 s12, s12, 0x181
	s_add_i32 s12, s12, -2
	s_lshr_b32 s13, s12, 6
	s_and_b32 s13, s13, 0x3fffffe
	s_sub_i32 s31, 7, s13
	s_and_b32 s42, s12, 0x7f
	s_lshr_b32 s42, s42, s31
	s_lshl_b32 s31, -1, s31
	s_andn2_b32 s12, s12, s31
	v_lshl_add_u32 v64, s12, 5, v156
	v_lshlrev_b32_e32 v64, s13, v64
	v_add_u32_e32 v64, s42, v64
	s_lshl_b32 s12, s40, 14
	v_ashrrev_i32_e32 v65, 31, v64
	s_and_b32 s12, s12, 0x1c000
	s_add_i32 s12, s94, s12
	v_lshlrev_b64 v[64:65], 11, v[64:65]
	v_lshl_add_u64 v[66:67], v[150:151], 0, v[64:65]
	s_mov_b32 m0, s12
	v_lshl_add_u64 v[64:65], v[152:153], 0, v[64:65]
	global_load_lds_dwordx4 v[66:67], off
	s_add_i32 m0, s12, 0x2000
	s_nop 0
	global_load_lds_dwordx4 v[64:65], off
	s_cmp_gt_u32 s33, 51
	s_cbranch_scc0 .LBB0_688
	s_branch .LBB0_689
